# attention softmax: 20-op canonicalising v_max tree replaced by 8-op v_max3 chain (bit-identical); on top of shw_gemm DPP reduction
# baseline (speedup 1.0000x reference)
.LBB0_991:
	s_mul_i32 s40, s41, 0x2200
	v_add_u32_e32 v173, s40, v172
	ds_read_b128 v[66:69], v173
	ds_read_b128 v[174:177], v173 offset:32
	ds_read_b128 v[178:181], v173 offset:64
	ds_read_b128 v[182:185], v173 offset:96
	s_waitcnt lgkmcnt(3)
	v_mfma_f32_32x32x16_bf16 v[66:81], v[66:69], v[82:85], 0
	s_waitcnt lgkmcnt(2)
	v_mfma_f32_32x32x16_bf16 v[66:81], v[174:177], v[86:89], v[66:81]
	s_waitcnt lgkmcnt(1)
	v_mfma_f32_32x32x16_bf16 v[66:81], v[178:181], v[90:93], v[66:81]
	s_waitcnt lgkmcnt(0)
	v_mfma_f32_32x32x16_bf16 v[66:81], v[182:185], v[94:97], v[66:81]
	ds_read_b128 v[174:177], v173 offset:128
	ds_read_b128 v[178:181], v173 offset:160
	ds_read_b128 v[182:185], v173 offset:192
	ds_read_b128 v[186:189], v173 offset:224
	s_waitcnt lgkmcnt(3)
	v_mfma_f32_32x32x16_bf16 v[66:81], v[174:177], v[98:101], v[66:81]
	s_waitcnt lgkmcnt(2)
	v_mfma_f32_32x32x16_bf16 v[66:81], v[178:181], v[102:105], v[66:81]
	s_waitcnt lgkmcnt(1)
	v_mfma_f32_32x32x16_bf16 v[66:81], v[182:185], v[106:109], v[66:81]
	s_waitcnt lgkmcnt(0)
	v_mfma_f32_32x32x16_bf16 v[66:81], v[186:189], v[110:113], v[66:81]
	s_and_b64 vcc, exec, s[24:25]
	s_mov_b64 s[0:1], -1
	s_cbranch_vccz .LBB0_993
	s_nop 8
	v_max3_f32 v173, v66, v67, v68
	v_max3_f32 v174, v69, v70, v71
	v_max3_f32 v175, v72, v73, v74
	v_max3_f32 v176, v75, v76, v77
	v_max3_f32 v177, v78, v79, v80
	v_max3_f32 v173, v173, v174, v81
	v_max3_f32 v175, v175, v176, v177
	v_max_f32_e32 v173, v173, v175
	s_mov_b64 s[0:1], 0
